# GEMM K-loop: all per-segment s_setprio flips removed (age arbitration only)
# speedup vs baseline: 1.0006x; 1.0006x over previous
.LBB0_810:
	s_add_i32 s6, s28, -2
	s_add_u32 s7, s2, 0x100
	s_addc_u32 s8, s3, 0
	s_add_u32 s2, s4, 0x80
	s_addc_u32 s3, s5, 0
	s_mov_b32 s4, 0
	s_add_i32 s9, s4, 2
	s_add_u32 s21, s2, 0x80
	s_addc_u32 s5, s3, 0
	s_add_i32 s29, 0, 0x10000
	s_cmp_eq_u32 s6, s4
	s_cselect_b32 s5, s23, s5
	s_cselect_b32 s4, s22, s21
	v_add_u32_e32 v0, s29, v204
	s_cselect_b32 s31, s25, s8
	s_cselect_b32 s30, s24, s7
	s_add_i32 s21, 0, 0x14000
	ds_read_b128 v[130:133], v0
	ds_read_b128 v[134:137], v0 offset:1024
	ds_read_b128 v[138:141], v0 offset:2048
	ds_read_b128 v[142:145], v0 offset:3072
	v_add_u32_e32 v0, s21, v204
	ds_read_b128 v[146:149], v0
	ds_read_b128 v[160:163], v0 offset:1024
	ds_read_b128 v[164:167], v0 offset:2048
	ds_read_b128 v[168:171], v0 offset:3072
	v_lshl_add_u64 v[176:177], s[2:3], 0, v[158:159]
	s_add_i32 m0, s27, 0xc000
	ds_read_b128 v[172:175], v205
	ds_read_b128 v[206:209], v205 offset:1024
	ds_read_b128 v[210:213], v205 offset:2048
	ds_read_b128 v[214:217], v205 offset:3072
	ds_read_b128 v[218:221], v205 offset:4096
	ds_read_b128 v[222:225], v205 offset:5120
	ds_read_b128 v[226:229], v205 offset:6144
	ds_read_b128 v[236:239], v205 offset:7168
	global_load_lds_dwordx4 v[176:177], off
	v_lshl_add_u64 v[176:177], s[2:3], 0, v[156:157]
	s_add_i32 m0, s27, 0xe000
	s_nop 0
	global_load_lds_dwordx4 v[176:177], off
	s_waitcnt vmcnt(8)
	s_waitcnt lgkmcnt(0)
	s_barrier
	s_waitcnt lgkmcnt(0)
	v_mfma_f32_16x16x32_bf16 v[126:129], v[130:133], v[172:175], 0
	v_mfma_f32_16x16x32_bf16 v[118:121], v[138:141], v[172:175], 0
	v_mfma_f32_16x16x32_bf16 v[110:113], v[130:133], v[210:213], 0
	v_mfma_f32_16x16x32_bf16 v[102:105], v[138:141], v[210:213], 0
	v_mfma_f32_16x16x32_bf16 v[94:97], v[130:133], v[218:221], 0
	v_mfma_f32_16x16x32_bf16 v[86:89], v[138:141], v[218:221], 0
	v_mfma_f32_16x16x32_bf16 v[78:81], v[130:133], v[226:229], 0
	v_mfma_f32_16x16x32_bf16 v[70:73], v[138:141], v[226:229], 0
	v_mfma_f32_16x16x32_bf16 v[126:129], v[134:137], v[206:209], v[126:129]
	v_mfma_f32_16x16x32_bf16 v[118:121], v[142:145], v[206:209], v[118:121]
	v_mfma_f32_16x16x32_bf16 v[110:113], v[134:137], v[214:217], v[110:113]
	v_mfma_f32_16x16x32_bf16 v[102:105], v[142:145], v[214:217], v[102:105]
	v_mfma_f32_16x16x32_bf16 v[94:97], v[134:137], v[222:225], v[94:97]
	v_mfma_f32_16x16x32_bf16 v[86:89], v[142:145], v[222:225], v[86:89]
	v_mfma_f32_16x16x32_bf16 v[78:81], v[134:137], v[236:239], v[78:81]
	v_mfma_f32_16x16x32_bf16 v[70:73], v[142:145], v[236:239], v[70:73]
	v_mfma_f32_16x16x32_bf16 v[122:125], v[146:149], v[172:175], 0
	v_mfma_f32_16x16x32_bf16 v[114:117], v[164:167], v[172:175], 0
	v_mfma_f32_16x16x32_bf16 v[106:109], v[146:149], v[210:213], 0
	v_mfma_f32_16x16x32_bf16 v[98:101], v[164:167], v[210:213], 0
	v_mfma_f32_16x16x32_bf16 v[90:93], v[146:149], v[218:221], 0
	v_mfma_f32_16x16x32_bf16 v[82:85], v[164:167], v[218:221], 0
	v_mfma_f32_16x16x32_bf16 v[74:77], v[146:149], v[226:229], 0
	v_mfma_f32_16x16x32_bf16 v[66:69], v[164:167], v[226:229], 0
	v_mfma_f32_16x16x32_bf16 v[122:125], v[160:163], v[206:209], v[122:125]
	v_mfma_f32_16x16x32_bf16 v[114:117], v[168:171], v[206:209], v[114:117]
	v_mfma_f32_16x16x32_bf16 v[106:109], v[160:163], v[214:217], v[106:109]
	v_mfma_f32_16x16x32_bf16 v[98:101], v[168:171], v[214:217], v[98:101]
	v_mfma_f32_16x16x32_bf16 v[90:93], v[160:163], v[222:225], v[90:93]
	v_mfma_f32_16x16x32_bf16 v[82:85], v[168:171], v[222:225], v[82:85]
	v_mfma_f32_16x16x32_bf16 v[74:77], v[160:163], v[236:239], v[74:77]
	v_mfma_f32_16x16x32_bf16 v[66:69], v[168:171], v[236:239], v[66:69]
	s_barrier
	s_add_i32 s29, s29, s44
	v_lshl_add_u64 v[176:177], s[30:31], 0, v[152:153]
	s_mov_b32 m0, s29
	ds_read_b128 v[172:175], v205 offset:16384
	ds_read_b128 v[206:209], v205 offset:17408
	ds_read_b128 v[210:213], v205 offset:18432
	ds_read_b128 v[214:217], v205 offset:19456
	ds_read_b128 v[218:221], v205 offset:20480
	ds_read_b128 v[222:225], v205 offset:21504
	ds_read_b128 v[226:229], v205 offset:22528
	ds_read_b128 v[236:239], v205 offset:23552
	global_load_lds_dwordx4 v[176:177], off
	s_add_i32 m0, s29, 0x2000
	v_lshl_add_u64 v[230:231], s[30:31], 0, v[154:155]
	s_add_u32 s30, s30, s12
	s_addc_u32 s31, s31, s13
	s_add_i32 s21, s21, s44
	global_load_lds_dwordx4 v[230:231], off
	v_lshl_add_u64 v[240:241], s[30:31], 0, v[152:153]
	s_mov_b32 m0, s21
	v_lshl_add_u64 v[242:243], s[30:31], 0, v[154:155]
	global_load_lds_dwordx4 v[240:241], off
	s_add_i32 m0, s21, 0x2000
	v_lshl_add_u64 v[244:245], s[4:5], 0, v[152:153]
	global_load_lds_dwordx4 v[242:243], off
	s_mov_b32 m0, s27
	v_lshl_add_u64 v[246:247], s[4:5], 0, v[154:155]
	global_load_lds_dwordx4 v[244:245], off
	s_mov_b32 m0, s45
	s_nop 0
	global_load_lds_dwordx4 v[246:247], off
	s_waitcnt vmcnt(8)
	s_waitcnt lgkmcnt(0)
	s_barrier
	s_waitcnt lgkmcnt(0)
	v_mfma_f32_16x16x32_bf16 v[62:65], v[130:133], v[172:175], 0
	v_mfma_f32_16x16x32_bf16 v[54:57], v[138:141], v[172:175], 0
	v_mfma_f32_16x16x32_bf16 v[46:49], v[130:133], v[210:213], 0
	v_mfma_f32_16x16x32_bf16 v[38:41], v[138:141], v[210:213], 0
	v_mfma_f32_16x16x32_bf16 v[30:33], v[130:133], v[218:221], 0
	v_mfma_f32_16x16x32_bf16 v[22:25], v[138:141], v[218:221], 0
	v_mfma_f32_16x16x32_bf16 v[14:17], v[130:133], v[226:229], 0
	v_mfma_f32_16x16x32_bf16 v[6:9], v[138:141], v[226:229], 0
	v_mfma_f32_16x16x32_bf16 v[62:65], v[134:137], v[206:209], v[62:65]
	v_mfma_f32_16x16x32_bf16 v[54:57], v[142:145], v[206:209], v[54:57]
	v_mfma_f32_16x16x32_bf16 v[46:49], v[134:137], v[214:217], v[46:49]
	v_mfma_f32_16x16x32_bf16 v[38:41], v[142:145], v[214:217], v[38:41]
	v_mfma_f32_16x16x32_bf16 v[30:33], v[134:137], v[222:225], v[30:33]
	v_mfma_f32_16x16x32_bf16 v[22:25], v[142:145], v[222:225], v[22:25]
	v_mfma_f32_16x16x32_bf16 v[14:17], v[134:137], v[236:239], v[14:17]
	v_mfma_f32_16x16x32_bf16 v[6:9], v[142:145], v[236:239], v[6:9]
	v_mfma_f32_16x16x32_bf16 v[58:61], v[146:149], v[172:175], 0
	v_mfma_f32_16x16x32_bf16 v[50:53], v[164:167], v[172:175], 0
	v_mfma_f32_16x16x32_bf16 v[42:45], v[146:149], v[210:213], 0
	v_mfma_f32_16x16x32_bf16 v[34:37], v[164:167], v[210:213], 0
	v_mfma_f32_16x16x32_bf16 v[26:29], v[146:149], v[218:221], 0
	v_mfma_f32_16x16x32_bf16 v[18:21], v[164:167], v[218:221], 0
	v_mfma_f32_16x16x32_bf16 v[10:13], v[146:149], v[226:229], 0
	v_mfma_f32_16x16x32_bf16 v[2:5], v[164:167], v[226:229], 0
	v_mfma_f32_16x16x32_bf16 v[58:61], v[160:163], v[206:209], v[58:61]
	v_mfma_f32_16x16x32_bf16 v[50:53], v[168:171], v[206:209], v[50:53]
	v_mfma_f32_16x16x32_bf16 v[42:45], v[160:163], v[214:217], v[42:45]
	v_mfma_f32_16x16x32_bf16 v[34:37], v[168:171], v[214:217], v[34:37]
	v_mfma_f32_16x16x32_bf16 v[26:29], v[160:163], v[222:225], v[26:29]
	v_mfma_f32_16x16x32_bf16 v[18:21], v[168:171], v[222:225], v[18:21]
	v_mfma_f32_16x16x32_bf16 v[10:13], v[160:163], v[236:239], v[10:13]
	v_mfma_f32_16x16x32_bf16 v[2:5], v[168:171], v[236:239], v[2:5]
	s_barrier
	s_add_i32 s21, 0, 0x18000
	v_add_u32_e32 v0, s21, v204
	s_add_i32 s29, 0, 0x1c000
	ds_read_b128 v[130:133], v0
	ds_read_b128 v[134:137], v0 offset:1024
	ds_read_b128 v[138:141], v0 offset:2048
	ds_read_b128 v[142:145], v0 offset:3072
	v_add_u32_e32 v0, s29, v204
	ds_read_b128 v[146:149], v0
	ds_read_b128 v[160:163], v0 offset:1024
	ds_read_b128 v[164:167], v0 offset:2048
	ds_read_b128 v[168:171], v0 offset:3072
	s_add_u32 s4, s4, s12
	s_addc_u32 s5, s5, s13
	s_mov_b32 m0, s46
	v_lshl_add_u64 v[248:249], s[4:5], 0, v[152:153]
	ds_read_b128 v[172:175], v205 offset:32768
	ds_read_b128 v[206:209], v205 offset:33792
	ds_read_b128 v[210:213], v205 offset:34816
	ds_read_b128 v[214:217], v205 offset:35840
	ds_read_b128 v[218:221], v205 offset:36864
	ds_read_b128 v[222:225], v205 offset:37888
	ds_read_b128 v[226:229], v205 offset:38912
	ds_read_b128 v[236:239], v205 offset:39936
	global_load_lds_dwordx4 v[248:249], off
	v_lshl_add_u64 v[248:249], s[4:5], 0, v[154:155]
	s_mov_b32 m0, s47
	s_nop 0
	global_load_lds_dwordx4 v[248:249], off
	s_waitcnt vmcnt(8)
	s_waitcnt lgkmcnt(0)
	s_barrier
	s_waitcnt lgkmcnt(0)
	v_mfma_f32_16x16x32_bf16 v[126:129], v[130:133], v[172:175], v[126:129]
	v_mfma_f32_16x16x32_bf16 v[118:121], v[138:141], v[172:175], v[118:121]
	v_mfma_f32_16x16x32_bf16 v[110:113], v[130:133], v[210:213], v[110:113]
	v_mfma_f32_16x16x32_bf16 v[102:105], v[138:141], v[210:213], v[102:105]
	v_mfma_f32_16x16x32_bf16 v[94:97], v[130:133], v[218:221], v[94:97]
	v_mfma_f32_16x16x32_bf16 v[86:89], v[138:141], v[218:221], v[86:89]
	v_mfma_f32_16x16x32_bf16 v[78:81], v[130:133], v[226:229], v[78:81]
	v_mfma_f32_16x16x32_bf16 v[70:73], v[138:141], v[226:229], v[70:73]
	v_mfma_f32_16x16x32_bf16 v[126:129], v[134:137], v[206:209], v[126:129]
	v_mfma_f32_16x16x32_bf16 v[118:121], v[142:145], v[206:209], v[118:121]
	v_mfma_f32_16x16x32_bf16 v[110:113], v[134:137], v[214:217], v[110:113]
	v_mfma_f32_16x16x32_bf16 v[102:105], v[142:145], v[214:217], v[102:105]
	v_mfma_f32_16x16x32_bf16 v[94:97], v[134:137], v[222:225], v[94:97]
	v_mfma_f32_16x16x32_bf16 v[86:89], v[142:145], v[222:225], v[86:89]
	v_mfma_f32_16x16x32_bf16 v[78:81], v[134:137], v[236:239], v[78:81]
	v_mfma_f32_16x16x32_bf16 v[70:73], v[142:145], v[236:239], v[70:73]
	v_mfma_f32_16x16x32_bf16 v[122:125], v[146:149], v[172:175], v[122:125]
	v_mfma_f32_16x16x32_bf16 v[114:117], v[164:167], v[172:175], v[114:117]
	v_mfma_f32_16x16x32_bf16 v[106:109], v[146:149], v[210:213], v[106:109]
	v_mfma_f32_16x16x32_bf16 v[98:101], v[164:167], v[210:213], v[98:101]
	v_mfma_f32_16x16x32_bf16 v[90:93], v[146:149], v[218:221], v[90:93]
	v_mfma_f32_16x16x32_bf16 v[82:85], v[164:167], v[218:221], v[82:85]
	v_mfma_f32_16x16x32_bf16 v[74:77], v[146:149], v[226:229], v[74:77]
	v_mfma_f32_16x16x32_bf16 v[66:69], v[164:167], v[226:229], v[66:69]
	v_mfma_f32_16x16x32_bf16 v[122:125], v[160:163], v[206:209], v[122:125]
	v_mfma_f32_16x16x32_bf16 v[114:117], v[168:171], v[206:209], v[114:117]
	v_mfma_f32_16x16x32_bf16 v[106:109], v[160:163], v[214:217], v[106:109]
	v_mfma_f32_16x16x32_bf16 v[98:101], v[168:171], v[214:217], v[98:101]
	v_mfma_f32_16x16x32_bf16 v[90:93], v[160:163], v[222:225], v[90:93]
	v_mfma_f32_16x16x32_bf16 v[82:85], v[168:171], v[222:225], v[82:85]
	v_mfma_f32_16x16x32_bf16 v[74:77], v[160:163], v[236:239], v[74:77]
	v_mfma_f32_16x16x32_bf16 v[66:69], v[168:171], v[236:239], v[66:69]
	s_barrier
	s_add_i32 s4, s21, s44
	v_lshl_add_u64 v[176:177], v[176:177], 0, s[92:93]
	s_mov_b32 m0, s4
	ds_read_b128 v[172:175], v205 offset:49152
	ds_read_b128 v[206:209], v205 offset:50176
	ds_read_b128 v[210:213], v205 offset:51200
	ds_read_b128 v[214:217], v205 offset:52224
	ds_read_b128 v[218:221], v205 offset:53248
	ds_read_b128 v[222:225], v205 offset:54272
	ds_read_b128 v[226:229], v205 offset:55296
	ds_read_b128 v[236:239], v205 offset:56320
	global_load_lds_dwordx4 v[176:177], off
	v_lshl_add_u64 v[176:177], v[230:231], 0, s[92:93]
	s_add_i32 m0, s4, 0x2000
	s_add_i32 s4, s29, s44
	global_load_lds_dwordx4 v[176:177], off
	v_lshl_add_u64 v[176:177], v[240:241], 0, s[92:93]
	s_mov_b32 m0, s4
	s_nop 0
	global_load_lds_dwordx4 v[176:177], off
	v_lshl_add_u64 v[176:177], v[242:243], 0, s[92:93]
	s_add_i32 m0, s4, 0x2000
	s_nop 0
	global_load_lds_dwordx4 v[176:177], off
	v_lshl_add_u64 v[176:177], v[244:245], 0, s[92:93]
	s_mov_b32 m0, s48
	s_nop 0
	global_load_lds_dwordx4 v[176:177], off
	v_lshl_add_u64 v[176:177], v[246:247], 0, s[92:93]
	s_mov_b32 m0, s49
	s_nop 0
	global_load_lds_dwordx4 v[176:177], off
	s_waitcnt vmcnt(8)
	s_waitcnt lgkmcnt(0)
	s_barrier
	s_waitcnt lgkmcnt(0)
	v_mfma_f32_16x16x32_bf16 v[62:65], v[130:133], v[172:175], v[62:65]
	v_mfma_f32_16x16x32_bf16 v[54:57], v[138:141], v[172:175], v[54:57]
	v_mfma_f32_16x16x32_bf16 v[46:49], v[130:133], v[210:213], v[46:49]
	v_mfma_f32_16x16x32_bf16 v[38:41], v[138:141], v[210:213], v[38:41]
	v_mfma_f32_16x16x32_bf16 v[30:33], v[130:133], v[218:221], v[30:33]
	v_mfma_f32_16x16x32_bf16 v[22:25], v[138:141], v[218:221], v[22:25]
	v_mfma_f32_16x16x32_bf16 v[14:17], v[130:133], v[226:229], v[14:17]
	v_mfma_f32_16x16x32_bf16 v[6:9], v[138:141], v[226:229], v[6:9]
	v_mfma_f32_16x16x32_bf16 v[62:65], v[134:137], v[206:209], v[62:65]
	v_mfma_f32_16x16x32_bf16 v[54:57], v[142:145], v[206:209], v[54:57]
	v_mfma_f32_16x16x32_bf16 v[46:49], v[134:137], v[214:217], v[46:49]
	v_mfma_f32_16x16x32_bf16 v[38:41], v[142:145], v[214:217], v[38:41]
	v_mfma_f32_16x16x32_bf16 v[30:33], v[134:137], v[222:225], v[30:33]
	v_mfma_f32_16x16x32_bf16 v[22:25], v[142:145], v[222:225], v[22:25]
	v_mfma_f32_16x16x32_bf16 v[14:17], v[134:137], v[236:239], v[14:17]
	v_mfma_f32_16x16x32_bf16 v[6:9], v[142:145], v[236:239], v[6:9]
	v_mfma_f32_16x16x32_bf16 v[58:61], v[146:149], v[172:175], v[58:61]
	v_mfma_f32_16x16x32_bf16 v[50:53], v[164:167], v[172:175], v[50:53]
	v_mfma_f32_16x16x32_bf16 v[42:45], v[146:149], v[210:213], v[42:45]
	v_mfma_f32_16x16x32_bf16 v[34:37], v[164:167], v[210:213], v[34:37]
	v_mfma_f32_16x16x32_bf16 v[26:29], v[146:149], v[218:221], v[26:29]
	v_mfma_f32_16x16x32_bf16 v[18:21], v[164:167], v[218:221], v[18:21]
	v_mfma_f32_16x16x32_bf16 v[10:13], v[146:149], v[226:229], v[10:13]
	v_mfma_f32_16x16x32_bf16 v[2:5], v[164:167], v[226:229], v[2:5]
	v_mfma_f32_16x16x32_bf16 v[58:61], v[160:163], v[206:209], v[58:61]
	v_mfma_f32_16x16x32_bf16 v[50:53], v[168:171], v[206:209], v[50:53]
	v_mfma_f32_16x16x32_bf16 v[42:45], v[160:163], v[214:217], v[42:45]
	v_mfma_f32_16x16x32_bf16 v[34:37], v[168:171], v[214:217], v[34:37]
	v_mfma_f32_16x16x32_bf16 v[26:29], v[160:163], v[222:225], v[26:29]
	v_mfma_f32_16x16x32_bf16 v[18:21], v[168:171], v[222:225], v[18:21]
	v_mfma_f32_16x16x32_bf16 v[10:13], v[160:163], v[236:239], v[10:13]
	v_mfma_f32_16x16x32_bf16 v[2:5], v[168:171], v[236:239], v[2:5]
	s_barrier
	s_add_u32 s7, s7, 0x100
	s_addc_u32 s8, s8, 0
	s_add_u32 s2, s2, 0x100
	s_addc_u32 s3, s3, 0
	s_cmp_ge_i32 s9, s28
	s_mov_b32 s4, s9
	s_cbranch_scc0 .LBB0_811
	s_branch .Lk_exit
.LBB0_811:
	s_add_i32 s9, s4, 2
	s_add_u32 s21, s2, 0x80
	s_addc_u32 s5, s3, 0
	s_add_i32 s29, 0, 0x10000
	s_cmp_eq_u32 s6, s4
	s_cselect_b32 s5, s23, s5
	s_cselect_b32 s4, s22, s21
	v_add_u32_e32 v0, s29, v204
	s_cselect_b32 s31, s25, s8
	s_cselect_b32 s30, s24, s7
	s_add_i32 s21, 0, 0x14000
	ds_read_b128 v[130:133], v0
	ds_read_b128 v[134:137], v0 offset:1024
	ds_read_b128 v[138:141], v0 offset:2048
	ds_read_b128 v[142:145], v0 offset:3072
	v_add_u32_e32 v0, s21, v204
	ds_read_b128 v[146:149], v0
	ds_read_b128 v[160:163], v0 offset:1024
	ds_read_b128 v[164:167], v0 offset:2048
	ds_read_b128 v[168:171], v0 offset:3072
	v_lshl_add_u64 v[176:177], s[2:3], 0, v[158:159]
	s_add_i32 m0, s27, 0xc000
	ds_read_b128 v[172:175], v205
	ds_read_b128 v[206:209], v205 offset:1024
	ds_read_b128 v[210:213], v205 offset:2048
	ds_read_b128 v[214:217], v205 offset:3072
	ds_read_b128 v[218:221], v205 offset:4096
	ds_read_b128 v[222:225], v205 offset:5120
	ds_read_b128 v[226:229], v205 offset:6144
	ds_read_b128 v[236:239], v205 offset:7168
	global_load_lds_dwordx4 v[176:177], off
	v_lshl_add_u64 v[176:177], s[2:3], 0, v[156:157]
	s_add_i32 m0, s27, 0xe000
	s_nop 0
	global_load_lds_dwordx4 v[176:177], off
	s_waitcnt vmcnt(8)
	s_waitcnt lgkmcnt(0)
	s_barrier
	s_waitcnt lgkmcnt(0)
	v_mfma_f32_16x16x32_bf16 v[126:129], v[130:133], v[172:175], v[126:129]
	v_mfma_f32_16x16x32_bf16 v[118:121], v[138:141], v[172:175], v[118:121]
	v_mfma_f32_16x16x32_bf16 v[110:113], v[130:133], v[210:213], v[110:113]
	v_mfma_f32_16x16x32_bf16 v[102:105], v[138:141], v[210:213], v[102:105]
	v_mfma_f32_16x16x32_bf16 v[94:97], v[130:133], v[218:221], v[94:97]
	v_mfma_f32_16x16x32_bf16 v[86:89], v[138:141], v[218:221], v[86:89]
	v_mfma_f32_16x16x32_bf16 v[78:81], v[130:133], v[226:229], v[78:81]
	v_mfma_f32_16x16x32_bf16 v[70:73], v[138:141], v[226:229], v[70:73]
	v_mfma_f32_16x16x32_bf16 v[126:129], v[134:137], v[206:209], v[126:129]
	v_mfma_f32_16x16x32_bf16 v[118:121], v[142:145], v[206:209], v[118:121]
	v_mfma_f32_16x16x32_bf16 v[110:113], v[134:137], v[214:217], v[110:113]
	v_mfma_f32_16x16x32_bf16 v[102:105], v[142:145], v[214:217], v[102:105]
	v_mfma_f32_16x16x32_bf16 v[94:97], v[134:137], v[222:225], v[94:97]
	v_mfma_f32_16x16x32_bf16 v[86:89], v[142:145], v[222:225], v[86:89]
	v_mfma_f32_16x16x32_bf16 v[78:81], v[134:137], v[236:239], v[78:81]
	v_mfma_f32_16x16x32_bf16 v[70:73], v[142:145], v[236:239], v[70:73]
	v_mfma_f32_16x16x32_bf16 v[122:125], v[146:149], v[172:175], v[122:125]
	v_mfma_f32_16x16x32_bf16 v[114:117], v[164:167], v[172:175], v[114:117]
	v_mfma_f32_16x16x32_bf16 v[106:109], v[146:149], v[210:213], v[106:109]
	v_mfma_f32_16x16x32_bf16 v[98:101], v[164:167], v[210:213], v[98:101]
	v_mfma_f32_16x16x32_bf16 v[90:93], v[146:149], v[218:221], v[90:93]
	v_mfma_f32_16x16x32_bf16 v[82:85], v[164:167], v[218:221], v[82:85]
	v_mfma_f32_16x16x32_bf16 v[74:77], v[146:149], v[226:229], v[74:77]
	v_mfma_f32_16x16x32_bf16 v[66:69], v[164:167], v[226:229], v[66:69]
	v_mfma_f32_16x16x32_bf16 v[122:125], v[160:163], v[206:209], v[122:125]
	v_mfma_f32_16x16x32_bf16 v[114:117], v[168:171], v[206:209], v[114:117]
	v_mfma_f32_16x16x32_bf16 v[106:109], v[160:163], v[214:217], v[106:109]
	v_mfma_f32_16x16x32_bf16 v[98:101], v[168:171], v[214:217], v[98:101]
	v_mfma_f32_16x16x32_bf16 v[90:93], v[160:163], v[222:225], v[90:93]
	v_mfma_f32_16x16x32_bf16 v[82:85], v[168:171], v[222:225], v[82:85]
	v_mfma_f32_16x16x32_bf16 v[74:77], v[160:163], v[236:239], v[74:77]
	v_mfma_f32_16x16x32_bf16 v[66:69], v[168:171], v[236:239], v[66:69]
	s_barrier
	s_add_i32 s29, s29, s44
	v_lshl_add_u64 v[176:177], s[30:31], 0, v[152:153]
	s_mov_b32 m0, s29
	ds_read_b128 v[172:175], v205 offset:16384
	ds_read_b128 v[206:209], v205 offset:17408
	ds_read_b128 v[210:213], v205 offset:18432
	ds_read_b128 v[214:217], v205 offset:19456
	ds_read_b128 v[218:221], v205 offset:20480
	ds_read_b128 v[222:225], v205 offset:21504
	ds_read_b128 v[226:229], v205 offset:22528
	ds_read_b128 v[236:239], v205 offset:23552
	global_load_lds_dwordx4 v[176:177], off
	s_add_i32 m0, s29, 0x2000
	v_lshl_add_u64 v[230:231], s[30:31], 0, v[154:155]
	s_add_u32 s30, s30, s12
	s_addc_u32 s31, s31, s13
	s_add_i32 s21, s21, s44
	global_load_lds_dwordx4 v[230:231], off
	v_lshl_add_u64 v[240:241], s[30:31], 0, v[152:153]
	s_mov_b32 m0, s21
	v_lshl_add_u64 v[242:243], s[30:31], 0, v[154:155]
	global_load_lds_dwordx4 v[240:241], off
	s_add_i32 m0, s21, 0x2000
	v_lshl_add_u64 v[244:245], s[4:5], 0, v[152:153]
	global_load_lds_dwordx4 v[242:243], off
	s_mov_b32 m0, s27
	v_lshl_add_u64 v[246:247], s[4:5], 0, v[154:155]
	global_load_lds_dwordx4 v[244:245], off
	s_mov_b32 m0, s45
	s_nop 0
	global_load_lds_dwordx4 v[246:247], off
	s_waitcnt vmcnt(8)
	s_waitcnt lgkmcnt(0)
	s_barrier
	s_waitcnt lgkmcnt(0)
	v_mfma_f32_16x16x32_bf16 v[62:65], v[130:133], v[172:175], v[62:65]
	v_mfma_f32_16x16x32_bf16 v[54:57], v[138:141], v[172:175], v[54:57]
	v_mfma_f32_16x16x32_bf16 v[46:49], v[130:133], v[210:213], v[46:49]
	v_mfma_f32_16x16x32_bf16 v[38:41], v[138:141], v[210:213], v[38:41]
	v_mfma_f32_16x16x32_bf16 v[30:33], v[130:133], v[218:221], v[30:33]
	v_mfma_f32_16x16x32_bf16 v[22:25], v[138:141], v[218:221], v[22:25]
	v_mfma_f32_16x16x32_bf16 v[14:17], v[130:133], v[226:229], v[14:17]
	v_mfma_f32_16x16x32_bf16 v[6:9], v[138:141], v[226:229], v[6:9]
	v_mfma_f32_16x16x32_bf16 v[62:65], v[134:137], v[206:209], v[62:65]
	v_mfma_f32_16x16x32_bf16 v[54:57], v[142:145], v[206:209], v[54:57]
	v_mfma_f32_16x16x32_bf16 v[46:49], v[134:137], v[214:217], v[46:49]
	v_mfma_f32_16x16x32_bf16 v[38:41], v[142:145], v[214:217], v[38:41]
	v_mfma_f32_16x16x32_bf16 v[30:33], v[134:137], v[222:225], v[30:33]
	v_mfma_f32_16x16x32_bf16 v[22:25], v[142:145], v[222:225], v[22:25]
	v_mfma_f32_16x16x32_bf16 v[14:17], v[134:137], v[236:239], v[14:17]
	v_mfma_f32_16x16x32_bf16 v[6:9], v[142:145], v[236:239], v[6:9]
	v_mfma_f32_16x16x32_bf16 v[58:61], v[146:149], v[172:175], v[58:61]
	v_mfma_f32_16x16x32_bf16 v[50:53], v[164:167], v[172:175], v[50:53]
	v_mfma_f32_16x16x32_bf16 v[42:45], v[146:149], v[210:213], v[42:45]
	v_mfma_f32_16x16x32_bf16 v[34:37], v[164:167], v[210:213], v[34:37]
	v_mfma_f32_16x16x32_bf16 v[26:29], v[146:149], v[218:221], v[26:29]
	v_mfma_f32_16x16x32_bf16 v[18:21], v[164:167], v[218:221], v[18:21]
	v_mfma_f32_16x16x32_bf16 v[10:13], v[146:149], v[226:229], v[10:13]
	v_mfma_f32_16x16x32_bf16 v[2:5], v[164:167], v[226:229], v[2:5]
	v_mfma_f32_16x16x32_bf16 v[58:61], v[160:163], v[206:209], v[58:61]
	v_mfma_f32_16x16x32_bf16 v[50:53], v[168:171], v[206:209], v[50:53]
	v_mfma_f32_16x16x32_bf16 v[42:45], v[160:163], v[214:217], v[42:45]
	v_mfma_f32_16x16x32_bf16 v[34:37], v[168:171], v[214:217], v[34:37]
	v_mfma_f32_16x16x32_bf16 v[26:29], v[160:163], v[222:225], v[26:29]
	v_mfma_f32_16x16x32_bf16 v[18:21], v[168:171], v[222:225], v[18:21]
	v_mfma_f32_16x16x32_bf16 v[10:13], v[160:163], v[236:239], v[10:13]
	v_mfma_f32_16x16x32_bf16 v[2:5], v[168:171], v[236:239], v[2:5]
	s_barrier
	s_add_i32 s21, 0, 0x18000
	v_add_u32_e32 v0, s21, v204
	s_add_i32 s29, 0, 0x1c000
	ds_read_b128 v[130:133], v0
	ds_read_b128 v[134:137], v0 offset:1024
	ds_read_b128 v[138:141], v0 offset:2048
	ds_read_b128 v[142:145], v0 offset:3072
	v_add_u32_e32 v0, s29, v204
	ds_read_b128 v[146:149], v0
	ds_read_b128 v[160:163], v0 offset:1024
	ds_read_b128 v[164:167], v0 offset:2048
	ds_read_b128 v[168:171], v0 offset:3072
	s_add_u32 s4, s4, s12
	s_addc_u32 s5, s5, s13
	s_mov_b32 m0, s46
	v_lshl_add_u64 v[248:249], s[4:5], 0, v[152:153]
	ds_read_b128 v[172:175], v205 offset:32768
	ds_read_b128 v[206:209], v205 offset:33792
	ds_read_b128 v[210:213], v205 offset:34816
	ds_read_b128 v[214:217], v205 offset:35840
	ds_read_b128 v[218:221], v205 offset:36864
	ds_read_b128 v[222:225], v205 offset:37888
	ds_read_b128 v[226:229], v205 offset:38912
	ds_read_b128 v[236:239], v205 offset:39936
	global_load_lds_dwordx4 v[248:249], off
	v_lshl_add_u64 v[248:249], s[4:5], 0, v[154:155]
	s_mov_b32 m0, s47
	s_nop 0
	global_load_lds_dwordx4 v[248:249], off
	s_waitcnt vmcnt(8)
	s_waitcnt lgkmcnt(0)
	s_barrier
	s_waitcnt lgkmcnt(0)
	v_mfma_f32_16x16x32_bf16 v[126:129], v[130:133], v[172:175], v[126:129]
	v_mfma_f32_16x16x32_bf16 v[118:121], v[138:141], v[172:175], v[118:121]
	v_mfma_f32_16x16x32_bf16 v[110:113], v[130:133], v[210:213], v[110:113]
	v_mfma_f32_16x16x32_bf16 v[102:105], v[138:141], v[210:213], v[102:105]
	v_mfma_f32_16x16x32_bf16 v[94:97], v[130:133], v[218:221], v[94:97]
	v_mfma_f32_16x16x32_bf16 v[86:89], v[138:141], v[218:221], v[86:89]
	v_mfma_f32_16x16x32_bf16 v[78:81], v[130:133], v[226:229], v[78:81]
	v_mfma_f32_16x16x32_bf16 v[70:73], v[138:141], v[226:229], v[70:73]
	v_mfma_f32_16x16x32_bf16 v[126:129], v[134:137], v[206:209], v[126:129]
	v_mfma_f32_16x16x32_bf16 v[118:121], v[142:145], v[206:209], v[118:121]
	v_mfma_f32_16x16x32_bf16 v[110:113], v[134:137], v[214:217], v[110:113]
	v_mfma_f32_16x16x32_bf16 v[102:105], v[142:145], v[214:217], v[102:105]
	v_mfma_f32_16x16x32_bf16 v[94:97], v[134:137], v[222:225], v[94:97]
	v_mfma_f32_16x16x32_bf16 v[86:89], v[142:145], v[222:225], v[86:89]
	v_mfma_f32_16x16x32_bf16 v[78:81], v[134:137], v[236:239], v[78:81]
	v_mfma_f32_16x16x32_bf16 v[70:73], v[142:145], v[236:239], v[70:73]
	v_mfma_f32_16x16x32_bf16 v[122:125], v[146:149], v[172:175], v[122:125]
	v_mfma_f32_16x16x32_bf16 v[114:117], v[164:167], v[172:175], v[114:117]
	v_mfma_f32_16x16x32_bf16 v[106:109], v[146:149], v[210:213], v[106:109]
	v_mfma_f32_16x16x32_bf16 v[98:101], v[164:167], v[210:213], v[98:101]
	v_mfma_f32_16x16x32_bf16 v[90:93], v[146:149], v[218:221], v[90:93]
	v_mfma_f32_16x16x32_bf16 v[82:85], v[164:167], v[218:221], v[82:85]
	v_mfma_f32_16x16x32_bf16 v[74:77], v[146:149], v[226:229], v[74:77]
	v_mfma_f32_16x16x32_bf16 v[66:69], v[164:167], v[226:229], v[66:69]
	v_mfma_f32_16x16x32_bf16 v[122:125], v[160:163], v[206:209], v[122:125]
	v_mfma_f32_16x16x32_bf16 v[114:117], v[168:171], v[206:209], v[114:117]
	v_mfma_f32_16x16x32_bf16 v[106:109], v[160:163], v[214:217], v[106:109]
	v_mfma_f32_16x16x32_bf16 v[98:101], v[168:171], v[214:217], v[98:101]
	v_mfma_f32_16x16x32_bf16 v[90:93], v[160:163], v[222:225], v[90:93]
	v_mfma_f32_16x16x32_bf16 v[82:85], v[168:171], v[222:225], v[82:85]
	v_mfma_f32_16x16x32_bf16 v[74:77], v[160:163], v[236:239], v[74:77]
	v_mfma_f32_16x16x32_bf16 v[66:69], v[168:171], v[236:239], v[66:69]
	s_barrier
	s_add_i32 s4, s21, s44
	v_lshl_add_u64 v[176:177], v[176:177], 0, s[92:93]
	s_mov_b32 m0, s4
	ds_read_b128 v[172:175], v205 offset:49152
	ds_read_b128 v[206:209], v205 offset:50176
	ds_read_b128 v[210:213], v205 offset:51200
	ds_read_b128 v[214:217], v205 offset:52224
	ds_read_b128 v[218:221], v205 offset:53248
	ds_read_b128 v[222:225], v205 offset:54272
	ds_read_b128 v[226:229], v205 offset:55296
	ds_read_b128 v[236:239], v205 offset:56320
	global_load_lds_dwordx4 v[176:177], off
	v_lshl_add_u64 v[176:177], v[230:231], 0, s[92:93]
	s_add_i32 m0, s4, 0x2000
	s_add_i32 s4, s29, s44
	global_load_lds_dwordx4 v[176:177], off
	v_lshl_add_u64 v[176:177], v[240:241], 0, s[92:93]
	s_mov_b32 m0, s4
	s_nop 0
	global_load_lds_dwordx4 v[176:177], off
	v_lshl_add_u64 v[176:177], v[242:243], 0, s[92:93]
	s_add_i32 m0, s4, 0x2000
	s_nop 0
	global_load_lds_dwordx4 v[176:177], off
	v_lshl_add_u64 v[176:177], v[244:245], 0, s[92:93]
	s_mov_b32 m0, s48
	s_nop 0
	global_load_lds_dwordx4 v[176:177], off
	v_lshl_add_u64 v[176:177], v[246:247], 0, s[92:93]
	s_mov_b32 m0, s49
	s_nop 0
	global_load_lds_dwordx4 v[176:177], off
	s_waitcnt vmcnt(8)
	s_waitcnt lgkmcnt(0)
	s_barrier
	s_waitcnt lgkmcnt(0)
	v_mfma_f32_16x16x32_bf16 v[62:65], v[130:133], v[172:175], v[62:65]
	v_mfma_f32_16x16x32_bf16 v[54:57], v[138:141], v[172:175], v[54:57]
	v_mfma_f32_16x16x32_bf16 v[46:49], v[130:133], v[210:213], v[46:49]
	v_mfma_f32_16x16x32_bf16 v[38:41], v[138:141], v[210:213], v[38:41]
	v_mfma_f32_16x16x32_bf16 v[30:33], v[130:133], v[218:221], v[30:33]
	v_mfma_f32_16x16x32_bf16 v[22:25], v[138:141], v[218:221], v[22:25]
	v_mfma_f32_16x16x32_bf16 v[14:17], v[130:133], v[226:229], v[14:17]
	v_mfma_f32_16x16x32_bf16 v[6:9], v[138:141], v[226:229], v[6:9]
	v_mfma_f32_16x16x32_bf16 v[62:65], v[134:137], v[206:209], v[62:65]
	v_mfma_f32_16x16x32_bf16 v[54:57], v[142:145], v[206:209], v[54:57]
	v_mfma_f32_16x16x32_bf16 v[46:49], v[134:137], v[214:217], v[46:49]
	v_mfma_f32_16x16x32_bf16 v[38:41], v[142:145], v[214:217], v[38:41]
	v_mfma_f32_16x16x32_bf16 v[30:33], v[134:137], v[222:225], v[30:33]
	v_mfma_f32_16x16x32_bf16 v[22:25], v[142:145], v[222:225], v[22:25]
	v_mfma_f32_16x16x32_bf16 v[14:17], v[134:137], v[236:239], v[14:17]
	v_mfma_f32_16x16x32_bf16 v[6:9], v[142:145], v[236:239], v[6:9]
	v_mfma_f32_16x16x32_bf16 v[58:61], v[146:149], v[172:175], v[58:61]
	v_mfma_f32_16x16x32_bf16 v[50:53], v[164:167], v[172:175], v[50:53]
	v_mfma_f32_16x16x32_bf16 v[42:45], v[146:149], v[210:213], v[42:45]
	v_mfma_f32_16x16x32_bf16 v[34:37], v[164:167], v[210:213], v[34:37]
	v_mfma_f32_16x16x32_bf16 v[26:29], v[146:149], v[218:221], v[26:29]
	v_mfma_f32_16x16x32_bf16 v[18:21], v[164:167], v[218:221], v[18:21]
	v_mfma_f32_16x16x32_bf16 v[10:13], v[146:149], v[226:229], v[10:13]
	v_mfma_f32_16x16x32_bf16 v[2:5], v[164:167], v[226:229], v[2:5]
	v_mfma_f32_16x16x32_bf16 v[58:61], v[160:163], v[206:209], v[58:61]
	v_mfma_f32_16x16x32_bf16 v[50:53], v[168:171], v[206:209], v[50:53]
	v_mfma_f32_16x16x32_bf16 v[42:45], v[160:163], v[214:217], v[42:45]
	v_mfma_f32_16x16x32_bf16 v[34:37], v[168:171], v[214:217], v[34:37]
	v_mfma_f32_16x16x32_bf16 v[26:29], v[160:163], v[222:225], v[26:29]
	v_mfma_f32_16x16x32_bf16 v[18:21], v[168:171], v[222:225], v[18:21]
	v_mfma_f32_16x16x32_bf16 v[10:13], v[160:163], v[236:239], v[10:13]
	v_mfma_f32_16x16x32_bf16 v[2:5], v[168:171], v[236:239], v[2:5]
	s_barrier
	s_add_u32 s7, s7, 0x100
	s_addc_u32 s8, s8, 0
	s_add_u32 s2, s2, 0x100
	s_addc_u32 s3, s3, 0
	s_cmp_ge_i32 s9, s28
	s_mov_b32 s4, s9
	s_cbranch_scc0 .LBB0_811
